# in-proj and ff1 staged-epilogue output stores marked nt (streaming) so operand tiles stay in L2
# speedup vs baseline: 1.0106x; 1.0106x over previous
; template <class F>
; DI void gemm8_epi_staged(f32x4 (&acc)[8][4], int m0, int n0, bf16_t* L0, F f, bf16_t* dst, size_t ld, int nmax) {
;     ...
; #pragma unroll
;     for (int it = 0; it < 8; ++it) {
;       const int idx = tid + 512 * it;
;       const int row = idx >> 5, ch = idx & 31;
;       const u32x4 v = *(const u32x4*)(L + row * 264 + ch * 8);
;       const int n = n0 + ch * 8;
;       if (n < nmax) *(u32x4*)(dst + (size_t)(m0 + half * 128 + row) * ld + n) = v;
;     }
;     __syncthreads();
.LBB0_137:
	s_or_b64 exec, exec, s[2:3]
	v_lshlrev_b32_e32 v0, 3, v77
	v_and_b32_e32 v0, 0xf8, v0
	v_or_b32_e32 v66, s9, v0
	v_lshl_add_u32 v68, v0, 1, s6
	v_lshlrev_b32_e32 v0, 1, v66
	v_cmp_gt_u32_e32 vcc, s96, v66
	v_lshl_add_u64 v[66:67], s[16:17], 0, v[0:1]
	v_add_u32_e32 v0, 0x200, v77
	v_add_u32_e32 v78, 0x400, v77
	v_add_u32_e32 v79, 0x600, v77
	v_add_u32_e32 v80, 0x800, v77
	v_add_u32_e32 v85, 0xa00, v77
	v_add_u32_e32 v86, 0xc00, v77
	v_add_u32_e32 v87, 0xe00, v77
	s_lshl_b32 s5, s5, 8
	v_ashrrev_i32_e32 v84, 5, v77
	v_ashrrev_i32_e32 v83, 5, v0
	v_ashrrev_i32_e32 v82, 5, v78
	v_ashrrev_i32_e32 v81, 5, v79
	v_ashrrev_i32_e32 v80, 5, v80
	v_ashrrev_i32_e32 v79, 5, v85
	v_ashrrev_i32_e32 v78, 5, v86
	v_ashrrev_i32_e32 v0, 5, v87
	s_waitcnt lgkmcnt(0)
	s_barrier
	s_and_saveexec_b64 s[2:3], vcc
	s_cbranch_execz .LBB0_139
	s_movk_i32 s9, 0x210
	v_mad_u64_u32 v[86:87], s[6:7], v84, s9, v[68:69]
	ds_read_b128 v[86:89], v86
	v_add_u32_e32 v85, s5, v84
	v_mad_i64_i32 v[90:91], s[6:7], v85, s35, v[66:67]
	v_add_u32_e32 v85, s5, v83
	s_waitcnt lgkmcnt(0)
	global_store_dwordx4 v[90:91], v[86:89], off nt
	v_mad_i64_i32 v[90:91], s[6:7], v85, s35, v[66:67]
	s_nop 0
	v_mad_u64_u32 v[86:87], s[6:7], v83, s9, v[68:69]
	ds_read_b128 v[86:89], v86
	v_add_u32_e32 v85, s5, v82
	s_waitcnt lgkmcnt(0)
	global_store_dwordx4 v[90:91], v[86:89], off nt
	s_nop 1
	v_mad_u64_u32 v[86:87], s[6:7], v82, s9, v[68:69]
	ds_read_b128 v[86:89], v86
	v_mad_i64_i32 v[90:91], s[6:7], v85, s35, v[66:67]
	v_add_u32_e32 v85, s5, v81
	s_waitcnt lgkmcnt(0)
	global_store_dwordx4 v[90:91], v[86:89], off nt
	v_mad_i64_i32 v[90:91], s[6:7], v85, s35, v[66:67]
	s_nop 0
	v_mad_u64_u32 v[86:87], s[6:7], v81, s9, v[68:69]
	ds_read_b128 v[86:89], v86
	v_add_u32_e32 v85, s5, v80
	s_waitcnt lgkmcnt(0)
	global_store_dwordx4 v[90:91], v[86:89], off nt
	s_nop 1
	v_mad_u64_u32 v[86:87], s[6:7], v80, s9, v[68:69]
	ds_read_b128 v[86:89], v86
	v_mad_i64_i32 v[90:91], s[6:7], v85, s35, v[66:67]
	v_add_u32_e32 v85, s5, v79
	s_waitcnt lgkmcnt(0)
	global_store_dwordx4 v[90:91], v[86:89], off nt
	v_mad_i64_i32 v[90:91], s[6:7], v85, s35, v[66:67]
	s_nop 0
	v_mad_u64_u32 v[86:87], s[6:7], v79, s9, v[68:69]
	ds_read_b128 v[86:89], v86
	v_add_u32_e32 v85, s5, v78
	s_waitcnt lgkmcnt(0)
	global_store_dwordx4 v[90:91], v[86:89], off nt
	s_nop 1
	v_mad_u64_u32 v[86:87], s[6:7], v78, s9, v[68:69]
	ds_read_b128 v[86:89], v86
	v_mad_i64_i32 v[90:91], s[6:7], v85, s35, v[66:67]
	v_add_u32_e32 v85, s5, v0
	s_waitcnt lgkmcnt(0)
	global_store_dwordx4 v[90:91], v[86:89], off nt
	v_mad_i64_i32 v[90:91], s[6:7], v85, s35, v[66:67]
	s_nop 0
	v_mad_u64_u32 v[86:87], s[6:7], v0, s9, v[68:69]
	ds_read_b128 v[86:89], v86
	s_waitcnt lgkmcnt(0)
	global_store_dwordx4 v[90:91], v[86:89], off nt

; template <class F>
; DI void gemm8_epi_staged(f32x4 (&acc)[8][4], int m0, int n0, bf16_t* L0, F f, bf16_t* dst, size_t ld, int nmax) {
;     ...
; #pragma unroll
;     for (int it = 0; it < 8; ++it) {
;       const int idx = tid + 512 * it;
;       const int row = idx >> 5, ch = idx & 31;
;       const u32x4 v = *(const u32x4*)(L + row * 264 + ch * 8);
;       const int n = n0 + ch * 8;
;       if (n < nmax) *(u32x4*)(dst + (size_t)(m0 + half * 128 + row) * ld + n) = v;
;     }
;     __syncthreads();
.LBB0_141:
	s_or_b64 exec, exec, s[6:7]
	s_waitcnt lgkmcnt(0)
	s_barrier
	s_and_saveexec_b64 s[2:3], vcc
	s_cbranch_execz .LBB0_128
	s_movk_i32 s9, 0x210
	v_mad_u64_u32 v[2:3], s[6:7], v84, s9, v[68:69]
	ds_read_b128 v[2:5], v2
	s_bitset1_b32 s5, 7
	v_add_u32_e32 v6, s5, v84
	v_mad_i64_i32 v[6:7], s[6:7], v6, s35, v[66:67]
	s_waitcnt lgkmcnt(0)
	global_store_dwordx4 v[6:7], v[2:5], off nt
	v_add_u32_e32 v6, s5, v83
	v_mad_i64_i32 v[6:7], s[6:7], v6, s35, v[66:67]
	v_mad_u64_u32 v[2:3], s[6:7], v83, s9, v[68:69]
	ds_read_b128 v[2:5], v2
	s_waitcnt lgkmcnt(0)
	global_store_dwordx4 v[6:7], v[2:5], off nt
	s_nop 1
	v_mad_u64_u32 v[2:3], s[6:7], v82, s9, v[68:69]
	ds_read_b128 v[2:5], v2
	v_add_u32_e32 v6, s5, v82
	v_mad_i64_i32 v[6:7], s[6:7], v6, s35, v[66:67]
	s_waitcnt lgkmcnt(0)
	global_store_dwordx4 v[6:7], v[2:5], off nt
	v_add_u32_e32 v6, s5, v81
	s_nop 0
	v_mad_u64_u32 v[2:3], s[6:7], v81, s9, v[68:69]
	ds_read_b128 v[2:5], v2
	v_mad_i64_i32 v[6:7], s[6:7], v6, s35, v[66:67]
	s_waitcnt lgkmcnt(0)
	global_store_dwordx4 v[6:7], v[2:5], off nt
	s_nop 1
	v_mad_u64_u32 v[2:3], s[6:7], v80, s9, v[68:69]
	ds_read_b128 v[2:5], v2
	v_add_u32_e32 v6, s5, v80
	v_mad_i64_i32 v[6:7], s[6:7], v6, s35, v[66:67]
	s_waitcnt lgkmcnt(0)
	global_store_dwordx4 v[6:7], v[2:5], off nt
	v_add_u32_e32 v6, s5, v79
	s_nop 0
	v_mad_u64_u32 v[2:3], s[6:7], v79, s9, v[68:69]
	ds_read_b128 v[2:5], v2
	v_mad_i64_i32 v[6:7], s[6:7], v6, s35, v[66:67]
	s_waitcnt lgkmcnt(0)
	global_store_dwordx4 v[6:7], v[2:5], off nt
	s_nop 1
	v_mad_u64_u32 v[2:3], s[6:7], v78, s9, v[68:69]
	ds_read_b128 v[2:5], v2
	v_add_u32_e32 v6, s5, v78
	v_mad_i64_i32 v[6:7], s[6:7], v6, s35, v[66:67]
	s_waitcnt lgkmcnt(0)
	global_store_dwordx4 v[6:7], v[2:5], off nt
	s_nop 1
	v_mad_u64_u32 v[2:3], s[6:7], v0, s9, v[68:69]
	ds_read_b128 v[2:5], v2
	v_add_u32_e32 v0, s5, v0
	v_mad_i64_i32 v[6:7], s[6:7], v0, s35, v[66:67]
	s_waitcnt lgkmcnt(0)
	global_store_dwordx4 v[6:7], v[2:5], off nt
	s_branch .LBB0_128

; template <class F>
; DI void gemm8_epi_staged(f32x4 (&acc)[8][4], int m0, int n0, bf16_t* L0, F f, bf16_t* dst, size_t ld, int nmax) {
;     ...
;     if (wm == half) {
; #pragma unroll
;       for (int i = 0; i < 8; ++i)
; #pragma unroll
;         for (int j = 0; j < 4; ++j) {
;           const int ml = i * 16 + (lane & 15);
;           const int nl = wn * 64 + j * 16 + (lane >> 4) * 4;
;           f32x4 a = acc[i][j];
;           f(m0 + half * 128 + ml, n0 + nl, a);
;           uint2 u;
;           u.x = pack2(a[0], a[1]);
;           u.y = pack2(a[2], a[3]);
;           *(uint2*)(L + ml * 264 + nl) = u;
;         }
;     }
;     __syncthreads();
; #pragma unroll
;     for (int it = 0; it < 8; ++it) {
;       const int idx = tid + 512 * it;
;       const int row = idx >> 5, ch = idx & 31;
;       const u32x4 v = *(const u32x4*)(L + row * 264 + ch * 8);
;       const int n = n0 + ch * 8;
;       if (n < nmax) *(u32x4*)(dst + (size_t)(m0 + half * 128 + row) * ld + n) = v;
;     }
;     __syncthreads();
; __global__ void __launch_bounds__(512, 2) mega(Params p) {
;     ...
;       gemm8_epi_staged(acc8, m0, n0, lds_all, [&](int, int, f32x4& a) {
;         float r0 = fmaxf(a[0], 0.f), r1 = fmaxf(a[1], 0.f), r2 = fmaxf(a[2], 0.f), r3 = fmaxf(a[3], 0.f);
;         a[0] = r0 * r0; a[1] = r1 * r1; a[2] = r2 * r2; a[3] = r3 * r3;
;       }, ubuf, 4096, 4096);
.LBB0_895:
	s_or_b64 exec, exec, s[2:3]
	v_lshlrev_b32_e32 v0, 3, v136
	v_and_b32_e32 v0, 0xf8, v0
	v_or_b32_e32 v2, s11, v0
	v_lshl_add_u32 v163, v0, 1, s7
	v_lshlrev_b32_e32 v0, 1, v2
	v_lshl_add_u64 v[2:3], s[16:17], 0, v[0:1]
	v_ashrrev_i32_e32 v0, 5, v136
	s_movk_i32 s2, 0x210
	v_mul_lo_u32 v141, v0, s2
	v_add_u32_e32 v142, v163, v141
	s_waitcnt lgkmcnt(0)
	s_barrier
	ds_read_b128 v[144:147], v142
	v_add_u32_e32 v148, s6, v0
	v_add_u32_e32 v141, 0x200, v136
	v_ashrrev_i32_e32 v149, 31, v148
	v_ashrrev_i32_e32 v141, 5, v141
	v_lshlrev_b64 v[148:149], 13, v[148:149]
	v_mul_lo_u32 v143, v141, s2
	v_lshl_add_u64 v[148:149], v[2:3], 0, v[148:149]
	v_add_u32_e32 v143, v163, v143
	s_waitcnt lgkmcnt(0)
	global_store_dwordx4 v[148:149], v[144:147], off nt
	ds_read_b128 v[144:147], v143
	v_add_u32_e32 v148, s6, v141
	v_ashrrev_i32_e32 v149, 31, v148
	v_lshlrev_b64 v[148:149], 13, v[148:149]
	v_lshl_add_u64 v[148:149], v[2:3], 0, v[148:149]
	s_waitcnt lgkmcnt(0)
	global_store_dwordx4 v[148:149], v[144:147], off nt
	s_nop 1
	v_add_u32_e32 v144, 0x400, v136
	v_ashrrev_i32_e32 v144, 5, v144
	v_mul_lo_u32 v145, v144, s2
	v_add_u32_e32 v146, v163, v145
	ds_read_b128 v[148:151], v146
	v_add_u32_e32 v152, s6, v144
	v_add_u32_e32 v145, 0x600, v136
	v_ashrrev_i32_e32 v153, 31, v152
	v_ashrrev_i32_e32 v145, 5, v145
	v_lshlrev_b64 v[152:153], 13, v[152:153]
	v_mul_lo_u32 v147, v145, s2
	v_lshl_add_u64 v[152:153], v[2:3], 0, v[152:153]
	v_add_u32_e32 v147, v163, v147
	s_waitcnt lgkmcnt(0)
	global_store_dwordx4 v[152:153], v[148:151], off nt
	ds_read_b128 v[148:151], v147
	v_add_u32_e32 v152, s6, v145
	v_ashrrev_i32_e32 v153, 31, v152
	v_lshlrev_b64 v[152:153], 13, v[152:153]
	v_lshl_add_u64 v[152:153], v[2:3], 0, v[152:153]
	s_waitcnt lgkmcnt(0)
	global_store_dwordx4 v[152:153], v[148:151], off nt
	s_nop 1
	v_add_u32_e32 v148, 0x800, v136
	v_ashrrev_i32_e32 v148, 5, v148
	v_mul_lo_u32 v149, v148, s2
	v_add_u32_e32 v150, v163, v149
	ds_read_b128 v[152:155], v150
	v_add_u32_e32 v156, s6, v148
	v_add_u32_e32 v149, 0xa00, v136
	v_ashrrev_i32_e32 v157, 31, v156
	v_ashrrev_i32_e32 v149, 5, v149
	v_lshlrev_b64 v[156:157], 13, v[156:157]
	v_mul_lo_u32 v151, v149, s2
	v_lshl_add_u64 v[156:157], v[2:3], 0, v[156:157]
	v_add_u32_e32 v151, v163, v151
	s_waitcnt lgkmcnt(0)
	global_store_dwordx4 v[156:157], v[152:155], off nt
	ds_read_b128 v[152:155], v151
	v_add_u32_e32 v156, s6, v149
	v_ashrrev_i32_e32 v157, 31, v156
	v_lshlrev_b64 v[156:157], 13, v[156:157]
	v_lshl_add_u64 v[156:157], v[2:3], 0, v[156:157]
	s_waitcnt lgkmcnt(0)
	global_store_dwordx4 v[156:157], v[152:155], off nt
	s_nop 1
	v_add_u32_e32 v152, 0xc00, v136
	v_ashrrev_i32_e32 v152, 5, v152
	v_mul_lo_u32 v153, v152, s2
	v_add_u32_e32 v154, v163, v153
	ds_read_b128 v[156:159], v154
	v_add_u32_e32 v160, s6, v152
	v_add_u32_e32 v153, 0xe00, v136
	v_ashrrev_i32_e32 v161, 31, v160
	v_ashrrev_i32_e32 v153, 5, v153
	v_lshlrev_b64 v[160:161], 13, v[160:161]
	v_mul_lo_u32 v155, v153, s2
	v_lshl_add_u64 v[160:161], v[2:3], 0, v[160:161]
	v_add_u32_e32 v155, v163, v155
	s_waitcnt lgkmcnt(0)
	global_store_dwordx4 v[160:161], v[156:159], off nt
	ds_read_b128 v[156:159], v155
	v_add_u32_e32 v160, s6, v153
	v_ashrrev_i32_e32 v161, 31, v160
	v_lshlrev_b64 v[160:161], 13, v[160:161]
	v_and_b32_e32 v136, 0xffffff00, v136
	s_movk_i32 s2, 0x100
	v_lshl_add_u64 v[160:161], v[2:3], 0, v[160:161]
	v_cmp_eq_u32_e32 vcc, s2, v136
	s_waitcnt lgkmcnt(0)
	global_store_dwordx4 v[160:161], v[156:159], off nt
	s_barrier
	s_and_saveexec_b64 s[2:3], vcc
	s_cbranch_execz .LBB0_886
	v_max_f32_e32 v120, 0, v120
	v_max_f32_e32 v121, 0, v121
	v_max_f32_e32 v122, 0, v122
	v_max_f32_e32 v123, 0, v123
	v_max_f32_e32 v116, 0, v116
	v_max_f32_e32 v117, 0, v117
	v_max_f32_e32 v118, 0, v118
	v_max_f32_e32 v119, 0, v119
	v_max_f32_e32 v136, 0, v137
	v_max_f32_e32 v137, 0, v138
	v_max_f32_e32 v138, 0, v139
	v_max_f32_e32 v139, 0, v140
	v_max_f32_e32 v132, 0, v132
	v_max_f32_e32 v133, 0, v133
	v_max_f32_e32 v134, 0, v134
	v_max_f32_e32 v135, 0, v135
	v_max_f32_e32 v128, 0, v128
	v_max_f32_e32 v129, 0, v129
	v_max_f32_e32 v130, 0, v130
	v_max_f32_e32 v131, 0, v131
	v_max_f32_e32 v124, 0, v124
	v_max_f32_e32 v125, 0, v125
	v_max_f32_e32 v126, 0, v126
	v_max_f32_e32 v127, 0, v127
	v_pk_mul_f32 v[120:121], v[120:121], v[120:121]
	v_pk_mul_f32 v[122:123], v[122:123], v[122:123]
	v_pk_mul_f32 v[116:117], v[116:117], v[116:117]
	v_pk_mul_f32 v[118:119], v[118:119], v[118:119]
	v_pk_mul_f32 v[136:137], v[136:137], v[136:137]
	v_pk_mul_f32 v[138:139], v[138:139], v[138:139]
	v_pk_mul_f32 v[132:133], v[132:133], v[132:133]
	v_pk_mul_f32 v[134:135], v[134:135], v[134:135]
	v_pk_mul_f32 v[128:129], v[128:129], v[128:129]
	v_pk_mul_f32 v[130:131], v[130:131], v[130:131]
	v_pk_mul_f32 v[124:125], v[124:125], v[124:125]
	v_pk_mul_f32 v[126:127], v[126:127], v[126:127]
	v_cvt_pk_bf16_f32 v120, v120, v121
	v_cvt_pk_bf16_f32 v121, v122, v123
	v_cvt_pk_bf16_f32 v116, v116, v117
	v_cvt_pk_bf16_f32 v117, v118, v119
	v_cvt_pk_bf16_f32 v136, v136, v137
	v_cvt_pk_bf16_f32 v137, v138, v139
	v_cvt_pk_bf16_f32 v132, v132, v133
	v_cvt_pk_bf16_f32 v133, v134, v135
	v_cvt_pk_bf16_f32 v128, v128, v129
	v_cvt_pk_bf16_f32 v129, v130, v131
	v_cvt_pk_bf16_f32 v124, v124, v125
	v_cvt_pk_bf16_f32 v125, v126, v127
	ds_write2_b64 v102, v[120:121], v[116:117] offset0:32 offset1:36
	v_max_f32_e32 v116, 0, v111
	v_max_f32_e32 v117, 0, v112
	v_max_f32_e32 v112, 0, v113
	v_max_f32_e32 v113, 0, v114
	ds_write2_b64 v115, v[136:137], v[132:133] offset1:4
	ds_write2_b64 v115, v[128:129], v[124:125] offset0:8 offset1:12
	v_pk_mul_f32 v[114:115], v[116:117], v[116:117]
	v_pk_mul_f32 v[112:113], v[112:113], v[112:113]
; template <class F>
; DI void gemm8_epi_staged(f32x4 (&acc)[8][4], int m0, int n0, bf16_t* L0, F f, bf16_t* dst, size_t ld, int nmax) {
;     ...
;     if (wm == half) {
; #pragma unroll
;       for (int i = 0; i < 8; ++i)
; #pragma unroll
;         for (int j = 0; j < 4; ++j) {
;           const int ml = i * 16 + (lane & 15);
;           const int nl = wn * 64 + j * 16 + (lane >> 4) * 4;
;           f32x4 a = acc[i][j];
;           f(m0 + half * 128 + ml, n0 + nl, a);
;           uint2 u;
;           u.x = pack2(a[0], a[1]);
;           u.y = pack2(a[2], a[3]);
;           *(uint2*)(L + ml * 264 + nl) = u;
;         }
;     }
; __global__ void __launch_bounds__(512, 2) mega(Params p) {
;     ...
;       gemm8_epi_staged(acc8, m0, n0, lds_all, [&](int, int, f32x4& a) {
;         float r0 = fmaxf(a[0], 0.f), r1 = fmaxf(a[1], 0.f), r2 = fmaxf(a[2], 0.f), r3 = fmaxf(a[3], 0.f);
;         a[0] = r0 * r0; a[1] = r1 * r1; a[2] = r2 * r2; a[3] = r3 * r3;
;       }, ubuf, 4096, 4096);
	v_cvt_pk_bf16_f32 v114, v114, v115
	v_cvt_pk_bf16_f32 v115, v112, v113
	v_max_f32_e32 v112, 0, v107
	v_max_f32_e32 v113, 0, v108
	v_max_f32_e32 v108, 0, v109
	v_max_f32_e32 v109, 0, v110
	v_pk_mul_f32 v[110:111], v[112:113], v[112:113]
	v_pk_mul_f32 v[108:109], v[108:109], v[108:109]
	v_cvt_pk_bf16_f32 v110, v110, v111
	v_cvt_pk_bf16_f32 v111, v108, v109
	ds_write2_b64 v102, v[114:115], v[110:111] offset0:40 offset1:44
	v_max_f32_e32 v102, 0, v103
	v_max_f32_e32 v103, 0, v104
	v_max_f32_e32 v104, 0, v105
	v_max_f32_e32 v105, 0, v106
	v_max_f32_e32 v98, 0, v98
	v_max_f32_e32 v99, 0, v99
	v_max_f32_e32 v100, 0, v100
	v_max_f32_e32 v101, 0, v101
	v_max_f32_e32 v94, 0, v94
	v_max_f32_e32 v95, 0, v95
	v_max_f32_e32 v96, 0, v96
	v_max_f32_e32 v97, 0, v97
	v_max_f32_e32 v90, 0, v90
	v_max_f32_e32 v91, 0, v91
	v_max_f32_e32 v92, 0, v92
	v_max_f32_e32 v93, 0, v93
	v_max_f32_e32 v86, 0, v86
	v_max_f32_e32 v87, 0, v87
	v_max_f32_e32 v88, 0, v88
	v_max_f32_e32 v89, 0, v89
	v_pk_mul_f32 v[102:103], v[102:103], v[102:103]
	v_pk_mul_f32 v[104:105], v[104:105], v[104:105]
	v_pk_mul_f32 v[98:99], v[98:99], v[98:99]
	v_pk_mul_f32 v[100:101], v[100:101], v[100:101]
	v_pk_mul_f32 v[94:95], v[94:95], v[94:95]
	v_pk_mul_f32 v[96:97], v[96:97], v[96:97]
	v_pk_mul_f32 v[90:91], v[90:91], v[90:91]
	v_pk_mul_f32 v[92:93], v[92:93], v[92:93]
	v_pk_mul_f32 v[86:87], v[86:87], v[86:87]
	v_pk_mul_f32 v[88:89], v[88:89], v[88:89]
	v_cvt_pk_bf16_f32 v102, v102, v103
	v_cvt_pk_bf16_f32 v103, v104, v105
	v_cvt_pk_bf16_f32 v98, v98, v99
	v_cvt_pk_bf16_f32 v99, v100, v101
	v_cvt_pk_bf16_f32 v94, v94, v95
	v_cvt_pk_bf16_f32 v95, v96, v97
	v_cvt_pk_bf16_f32 v90, v90, v91
	v_cvt_pk_bf16_f32 v91, v92, v93
	v_cvt_pk_bf16_f32 v86, v86, v87
	v_cvt_pk_bf16_f32 v87, v88, v89
	v_max_f32_e32 v88, 0, v81
	v_max_f32_e32 v89, 0, v82
	v_max_f32_e32 v82, 0, v83
	v_max_f32_e32 v83, 0, v84
	ds_write2_b64 v85, v[102:103], v[98:99] offset0:64 offset1:68
	ds_write2_b64 v85, v[94:95], v[90:91] offset0:72 offset1:76
	v_pk_mul_f32 v[84:85], v[88:89], v[88:89]
	v_pk_mul_f32 v[82:83], v[82:83], v[82:83]
	v_cvt_pk_bf16_f32 v84, v84, v85
	v_cvt_pk_bf16_f32 v85, v82, v83
	v_max_f32_e32 v82, 0, v77
	v_max_f32_e32 v83, 0, v78
	v_max_f32_e32 v78, 0, v79
	v_max_f32_e32 v79, 0, v80
	v_pk_mul_f32 v[80:81], v[82:83], v[82:83]
	v_pk_mul_f32 v[78:79], v[78:79], v[78:79]
	v_cvt_pk_bf16_f32 v80, v80, v81
	v_cvt_pk_bf16_f32 v81, v78, v79
	v_max_f32_e32 v78, 0, v73
	v_max_f32_e32 v79, 0, v74
	v_max_f32_e32 v74, 0, v75
	v_max_f32_e32 v75, 0, v76
	v_pk_mul_f32 v[76:77], v[78:79], v[78:79]
	v_pk_mul_f32 v[74:75], v[74:75], v[74:75]
	v_cvt_pk_bf16_f32 v76, v76, v77
	v_cvt_pk_bf16_f32 v77, v74, v75
	ds_write2_b64 v68, v[86:87], v[84:85] offset0:96 offset1:100
	ds_write2_b64 v68, v[80:81], v[76:77] offset0:104 offset1:108
	v_max_f32_e32 v68, 0, v69
	v_max_f32_e32 v69, 0, v70
	v_max_f32_e32 v70, 0, v71
	v_max_f32_e32 v71, 0, v72
	v_max_f32_e32 v64, 0, v64
	v_max_f32_e32 v65, 0, v65
	v_max_f32_e32 v66, 0, v66
	v_max_f32_e32 v67, 0, v67
	v_max_f32_e32 v60, 0, v60
	v_max_f32_e32 v61, 0, v61
	v_max_f32_e32 v62, 0, v62
	v_max_f32_e32 v63, 0, v63
	v_max_f32_e32 v56, 0, v56
	v_max_f32_e32 v57, 0, v57
	v_max_f32_e32 v58, 0, v58
	v_max_f32_e32 v59, 0, v59
	v_max_f32_e32 v52, 0, v52
	v_max_f32_e32 v53, 0, v53
	v_max_f32_e32 v54, 0, v54
	v_max_f32_e32 v55, 0, v55
	v_pk_mul_f32 v[68:69], v[68:69], v[68:69]
	v_pk_mul_f32 v[70:71], v[70:71], v[70:71]
	v_pk_mul_f32 v[64:65], v[64:65], v[64:65]
	v_pk_mul_f32 v[66:67], v[66:67], v[66:67]
	v_pk_mul_f32 v[60:61], v[60:61], v[60:61]
	v_pk_mul_f32 v[62:63], v[62:63], v[62:63]
	v_pk_mul_f32 v[56:57], v[56:57], v[56:57]
	v_pk_mul_f32 v[58:59], v[58:59], v[58:59]
	v_pk_mul_f32 v[52:53], v[52:53], v[52:53]
; template <class F>
; DI void gemm8_epi_staged(f32x4 (&acc)[8][4], int m0, int n0, bf16_t* L0, F f, bf16_t* dst, size_t ld, int nmax) {
;     ...
;     if (wm == half) {
; #pragma unroll
;       for (int i = 0; i < 8; ++i)
; #pragma unroll
;         for (int j = 0; j < 4; ++j) {
;           const int ml = i * 16 + (lane & 15);
;           const int nl = wn * 64 + j * 16 + (lane >> 4) * 4;
;           f32x4 a = acc[i][j];
;           f(m0 + half * 128 + ml, n0 + nl, a);
;           uint2 u;
;           u.x = pack2(a[0], a[1]);
;           u.y = pack2(a[2], a[3]);
;           *(uint2*)(L + ml * 264 + nl) = u;
;         }
;     }
; __global__ void __launch_bounds__(512, 2) mega(Params p) {
;     ...
;       gemm8_epi_staged(acc8, m0, n0, lds_all, [&](int, int, f32x4& a) {
;         float r0 = fmaxf(a[0], 0.f), r1 = fmaxf(a[1], 0.f), r2 = fmaxf(a[2], 0.f), r3 = fmaxf(a[3], 0.f);
;         a[0] = r0 * r0; a[1] = r1 * r1; a[2] = r2 * r2; a[3] = r3 * r3;
;       }, ubuf, 4096, 4096);
	v_pk_mul_f32 v[54:55], v[54:55], v[54:55]
	v_cvt_pk_bf16_f32 v68, v68, v69
	v_cvt_pk_bf16_f32 v69, v70, v71
	v_cvt_pk_bf16_f32 v64, v64, v65
	v_cvt_pk_bf16_f32 v65, v66, v67
	v_cvt_pk_bf16_f32 v60, v60, v61
	v_cvt_pk_bf16_f32 v61, v62, v63
	v_cvt_pk_bf16_f32 v56, v56, v57
	v_cvt_pk_bf16_f32 v57, v58, v59
	v_cvt_pk_bf16_f32 v52, v52, v53
	v_cvt_pk_bf16_f32 v53, v54, v55
	v_max_f32_e32 v54, 0, v47
	v_max_f32_e32 v55, 0, v48
	v_max_f32_e32 v48, 0, v49
	v_max_f32_e32 v49, 0, v50
	ds_write2_b64 v51, v[68:69], v[64:65] offset0:128 offset1:132
	ds_write2_b64 v51, v[60:61], v[56:57] offset0:136 offset1:140
	v_pk_mul_f32 v[50:51], v[54:55], v[54:55]
	v_pk_mul_f32 v[48:49], v[48:49], v[48:49]
	v_cvt_pk_bf16_f32 v50, v50, v51
	v_cvt_pk_bf16_f32 v51, v48, v49
	v_max_f32_e32 v48, 0, v43
	v_max_f32_e32 v49, 0, v44
	v_max_f32_e32 v44, 0, v45
	v_max_f32_e32 v45, 0, v46
	v_pk_mul_f32 v[46:47], v[48:49], v[48:49]
	v_pk_mul_f32 v[44:45], v[44:45], v[44:45]
	v_cvt_pk_bf16_f32 v46, v46, v47
	v_cvt_pk_bf16_f32 v47, v44, v45
	v_max_f32_e32 v44, 0, v39
	v_max_f32_e32 v45, 0, v40
	v_max_f32_e32 v40, 0, v41
	v_max_f32_e32 v41, 0, v42
	v_pk_mul_f32 v[42:43], v[44:45], v[44:45]
	v_pk_mul_f32 v[40:41], v[40:41], v[40:41]
	v_cvt_pk_bf16_f32 v42, v42, v43
	v_cvt_pk_bf16_f32 v43, v40, v41
	ds_write2_b64 v34, v[52:53], v[50:51] offset0:160 offset1:164
	ds_write2_b64 v34, v[46:47], v[42:43] offset0:168 offset1:172
	v_max_f32_e32 v34, 0, v35
	v_max_f32_e32 v35, 0, v36
	v_max_f32_e32 v36, 0, v37
	v_max_f32_e32 v37, 0, v38
	v_max_f32_e32 v30, 0, v30
	v_max_f32_e32 v31, 0, v31
	v_max_f32_e32 v32, 0, v32
	v_max_f32_e32 v33, 0, v33
	v_max_f32_e32 v26, 0, v26
	v_max_f32_e32 v27, 0, v27
	v_max_f32_e32 v28, 0, v28
	v_max_f32_e32 v29, 0, v29
	v_max_f32_e32 v22, 0, v22
	v_max_f32_e32 v23, 0, v23
	v_max_f32_e32 v24, 0, v24
	v_max_f32_e32 v25, 0, v25
	v_max_f32_e32 v18, 0, v18
	v_max_f32_e32 v19, 0, v19
	v_max_f32_e32 v20, 0, v20
	v_max_f32_e32 v21, 0, v21
	v_pk_mul_f32 v[34:35], v[34:35], v[34:35]
	v_pk_mul_f32 v[36:37], v[36:37], v[36:37]
	v_pk_mul_f32 v[30:31], v[30:31], v[30:31]
	v_pk_mul_f32 v[32:33], v[32:33], v[32:33]
	v_pk_mul_f32 v[26:27], v[26:27], v[26:27]
	v_pk_mul_f32 v[28:29], v[28:29], v[28:29]
	v_pk_mul_f32 v[22:23], v[22:23], v[22:23]
	v_pk_mul_f32 v[24:25], v[24:25], v[24:25]
	v_pk_mul_f32 v[18:19], v[18:19], v[18:19]
	v_pk_mul_f32 v[20:21], v[20:21], v[20:21]
	v_cvt_pk_bf16_f32 v34, v34, v35
	v_cvt_pk_bf16_f32 v35, v36, v37
	v_cvt_pk_bf16_f32 v30, v30, v31
	v_cvt_pk_bf16_f32 v31, v32, v33
	v_cvt_pk_bf16_f32 v26, v26, v27
	v_cvt_pk_bf16_f32 v27, v28, v29
	v_cvt_pk_bf16_f32 v22, v22, v23
	v_cvt_pk_bf16_f32 v23, v24, v25
	v_cvt_pk_bf16_f32 v18, v18, v19
	v_cvt_pk_bf16_f32 v19, v20, v21
	v_max_f32_e32 v20, 0, v13
	v_max_f32_e32 v21, 0, v14
	v_max_f32_e32 v14, 0, v15
	v_max_f32_e32 v15, 0, v16
	ds_write2_b64 v17, v[34:35], v[30:31] offset0:192 offset1:196
	ds_write2_b64 v17, v[26:27], v[22:23] offset0:200 offset1:204
	v_pk_mul_f32 v[16:17], v[20:21], v[20:21]
	v_pk_mul_f32 v[14:15], v[14:15], v[14:15]
	v_cvt_pk_bf16_f32 v16, v16, v17
	v_cvt_pk_bf16_f32 v17, v14, v15
	v_max_f32_e32 v14, 0, v9
	v_max_f32_e32 v15, 0, v10
	v_max_f32_e32 v10, 0, v11
	v_max_f32_e32 v11, 0, v12
	v_pk_mul_f32 v[12:13], v[14:15], v[14:15]
	v_pk_mul_f32 v[10:11], v[10:11], v[10:11]
	v_max_f32_e32 v5, v5, v5
	v_cvt_pk_bf16_f32 v12, v12, v13
	v_cvt_pk_bf16_f32 v13, v10, v11
	v_max_f32_e32 v10, 0, v7
	v_max_f32_e32 v11, 0, v8
	v_max_f32_e32 v4, 0, v4
	v_max_f32_e32 v5, 0, v5
	v_pk_mul_f32 v[8:9], v[10:11], v[10:11]
	v_pk_mul_f32 v[4:5], v[4:5], v[4:5]
	v_cvt_pk_bf16_f32 v8, v8, v9
	v_cvt_pk_bf16_f32 v9, v4, v5
	ds_write2_b64 v6, v[18:19], v[16:17] offset0:224 offset1:228
	ds_write2_b64 v6, v[12:13], v[8:9] offset0:232 offset1:236
	s_branch .LBB0_886
